# RG-LRU task loop: the loop-top vmcnt(0) (which only waited for the previous task's output-store acks) moved into the first-iteration parameter block
# baseline (speedup 1.0000x reference)
.LBB0_307:
	s_and_b32 s41, s40, 7
	s_cmp_eq_u32 s41, s2
	s_cbranch_scc1 .LBB0_309
	s_lshl_b32 s0, s41, 6
	v_or_b32_e32 v18, s0, v121
	s_mov_b64 s[42:43], s[52:53]
	v_readlane_b32 s52, v254, 60
	v_lshlrev_b32_e32 v38, 2, v18
	v_mov_b32_e32 v39, v196
	v_readlane_b32 s64, v255, 8
	v_readlane_b32 s65, v255, 9
	v_readlane_b32 s53, v254, 61
	v_readlane_b32 s54, v254, 62
	v_readlane_b32 s55, v254, 63
	v_readlane_b32 s56, v255, 0
	v_readlane_b32 s57, v255, 1
	v_readlane_b32 s58, v255, 2
	v_readlane_b32 s59, v255, 3
	v_readlane_b32 s60, v255, 4
	v_readlane_b32 s61, v255, 5
	v_readlane_b32 s62, v255, 6
	v_readlane_b32 s63, v255, 7
	v_readlane_b32 s66, v255, 10
	v_readlane_b32 s67, v255, 11
	v_lshl_add_u64 v[50:51], s[64:65], 0, v[38:39]
	s_mov_b64 s[16:17], 0x1000
	s_movk_i32 s1, 0x1000
	s_nop 1
	global_load_dwordx4 v[22:25], v38, s[66:67] offset:16
	global_load_dwordx4 v[18:21], v38, s[64:65] offset:16
	global_load_dwordx4 v[30:33], v38, s[66:67]
	global_load_dwordx4 v[26:29], v38, s[64:65]
	global_load_dwordx4 v[34:37], v38, s[64:65] offset:2064
	s_nop 0
	global_load_dwordx4 v[38:41], v38, s[64:65] offset:2048
	v_lshl_add_u64 v[42:43], v[50:51], 0, s[16:17]
	v_add_co_u32_e32 v52, vcc, s1, v50
	s_mov_b64 s[16:17], 0x1800
	v_or_b32_e32 v58, s0, v120
	v_readlane_b32 s52, v255, 12
	v_readlane_b32 s0, v255, 43
	v_addc_co_u32_e32 v53, vcc, 0, v51, vcc
	v_lshl_add_u64 v[50:51], v[50:51], 0, s[16:17]
	v_lshlrev_b32_e32 v58, 2, v58
	v_readlane_b32 s54, v255, 14
	v_readlane_b32 s55, v255, 15
	v_readlane_b32 s1, v255, 44
	global_load_dwordx4 v[46:49], v[52:53], off
	s_nop 0
	global_load_dwordx4 v[42:45], v[42:43], off offset:16
	s_nop 0
	global_load_dwordx4 v[54:57], v[52:53], off offset:2048
	s_nop 0
	global_load_dwordx4 v[50:53], v[50:51], off offset:16
	v_readlane_b32 s58, v255, 18
	v_readlane_b32 s59, v255, 19
	global_load_dword v153, v58, s[54:55]
	s_nop 3
	global_load_dword v154, v58, s[58:59]
	global_load_dword v155, v58, s[0:1]
	s_lshl_b32 s0, s41, 13
	s_mov_b32 s1, s46
	v_lshl_add_u64 v[74:75], v[96:97], 0, s[0:1]
	global_load_dwordx4 v[70:73], v[74:75], off
	global_load_dwordx4 v[66:69], v[74:75], off offset:64
	global_load_dwordx4 v[62:65], v[74:75], off offset:2048
	global_load_dwordx4 v[58:61], v[74:75], off offset:2112
	v_add_co_u32_e32 v74, vcc, 0x1000, v74
	v_readlane_b32 s60, v255, 20
	s_nop 0
	v_addc_co_u32_e32 v75, vcc, 0, v75, vcc
	global_load_dwordx4 v[86:89], v[74:75], off
	global_load_dwordx4 v[82:85], v[74:75], off offset:64
	global_load_dwordx4 v[78:81], v[74:75], off offset:2048
	s_nop 0
	global_load_dwordx4 v[74:77], v[74:75], off offset:2112
	v_readlane_b32 s61, v255, 21
	v_readlane_b32 s62, v255, 22
	v_readlane_b32 s63, v255, 23
	v_readlane_b32 s53, v255, 13
	v_readlane_b32 s62, v255, 51
	v_readlane_b32 s60, v255, 49
	s_mov_b64 s[52:53], s[42:43]
	v_readlane_b32 s63, v255, 52
	v_readlane_b32 s61, v255, 50
	s_mov_b32 s2, s41
	v_readlane_b32 s56, v255, 16
	v_readlane_b32 s57, v255, 17
	v_readlane_b32 s64, v255, 24
	v_readlane_b32 s65, v255, 25
	v_readlane_b32 s66, v255, 26
	v_readlane_b32 s67, v255, 27
	s_waitcnt vmcnt(0)
.LBB0_309:
	v_lshlrev_b32_e32 v98, 16, v6
	v_and_b32_e32 v99, 0xffff0000, v6
	v_pk_fma_f32 v[98:99], v[26:27], v[98:99], v[30:31]
	v_lshlrev_b32_e32 v100, 16, v2
	v_and_b32_e32 v101, 0xffff0000, v2
	v_pk_fma_f32 v[98:99], v[38:39], v[100:101], v[98:99]
	v_lshlrev_b32_e32 v100, 16, v10
	v_and_b32_e32 v101, 0xffff0000, v10
	v_pk_fma_f32 v[98:99], v[46:47], v[100:101], v[98:99]
	v_lshlrev_b32_e32 v100, 16, v14
	v_and_b32_e32 v101, 0xffff0000, v14
	v_pk_fma_f32 v[98:99], v[54:55], v[100:101], v[98:99]
	v_lshlrev_b32_e32 v100, 16, v7
	v_and_b32_e32 v101, 0xffff0000, v7
	v_pk_fma_f32 v[100:101], v[28:29], v[100:101], v[32:33]
	v_lshlrev_b32_e32 v102, 16, v3
	v_and_b32_e32 v103, 0xffff0000, v3
	v_pk_fma_f32 v[100:101], v[40:41], v[102:103], v[100:101]
	v_lshlrev_b32_e32 v102, 16, v11
	v_and_b32_e32 v103, 0xffff0000, v11
	v_pk_fma_f32 v[100:101], v[48:49], v[102:103], v[100:101]
	v_lshlrev_b32_e32 v102, 16, v15
	v_and_b32_e32 v103, 0xffff0000, v15
	s_barrier
	v_pk_fma_f32 v[100:101], v[56:57], v[102:103], v[100:101]
	v_lshlrev_b32_e32 v102, 16, v8
	v_and_b32_e32 v103, 0xffff0000, v8
	s_load_dword s15, s[78:79], 0x0
	v_pk_fma_f32 v[102:103], v[18:19], v[102:103], v[22:23]
	v_lshlrev_b32_e32 v104, 16, v4
	v_and_b32_e32 v105, 0xffff0000, v4
	v_pk_fma_f32 v[102:103], v[34:35], v[104:105], v[102:103]
	v_lshlrev_b32_e32 v104, 16, v12
	v_and_b32_e32 v105, 0xffff0000, v12
	v_pk_fma_f32 v[102:103], v[42:43], v[104:105], v[102:103]
	v_lshlrev_b32_e32 v104, 16, v16
	v_and_b32_e32 v105, 0xffff0000, v16
	v_pk_fma_f32 v[102:103], v[50:51], v[104:105], v[102:103]
	v_lshlrev_b32_e32 v104, 16, v9
	v_and_b32_e32 v105, 0xffff0000, v9
	v_pk_fma_f32 v[104:105], v[20:21], v[104:105], v[24:25]
	v_lshlrev_b32_e32 v106, 16, v5
	v_and_b32_e32 v107, 0xffff0000, v5
	s_waitcnt lgkmcnt(0)
	s_add_i32 s15, s15, s40
	v_pk_fma_f32 v[104:105], v[36:37], v[106:107], v[104:105]
	v_lshlrev_b32_e32 v106, 16, v13
	v_and_b32_e32 v107, 0xffff0000, v13
	s_cmpk_gt_i32 s15, 0x7ff
	v_pk_fma_f32 v[104:105], v[44:45], v[106:107], v[104:105]
	v_lshlrev_b32_e32 v106, 16, v17
	v_and_b32_e32 v107, 0xffff0000, v17
	s_cselect_b64 s[16:17], -1, 0
	v_pk_fma_f32 v[104:105], v[52:53], v[106:107], v[104:105]
	v_cvt_pk_bf16_f32 v106, v98, v99
	v_cvt_pk_bf16_f32 v107, v100, v101
	v_cvt_pk_bf16_f32 v108, v102, v103
	v_add_u32_e32 v110, v122, v90
	v_cvt_pk_bf16_f32 v109, v104, v105
	s_and_b64 vcc, exec, s[16:17]
	ds_write_b128 v110, v[106:109]
	ds_write_b128 v123, v[98:101] offset:9216
	ds_write_b128 v123, v[102:105] offset:9232
	s_cbranch_vccnz .LBB0_319
	s_lshl_b32 s0, s15, 8
	s_and_b32 s42, s15, 0xffffffc0
	s_and_b32 s33, s0, 0x3800
	s_lshl_b32 s0, s15, 7
	v_add_u32_e32 v14, s42, v124
	s_and_b32 s0, s0, 0x380
	s_mov_b32 s1, s46
	v_mov_b32_e32 v2, v196
	v_mov_b32_e32 v3, v196
	v_lshl_add_u64 v[98:99], v[92:93], 0, s[0:1]
	v_cmp_lt_i32_e32 vcc, -1, v14
	v_mov_b64_e32 v[6:7], v[2:3]
	v_mov_b64_e32 v[8:9], v[2:3]
	s_and_saveexec_b64 s[0:1], vcc
	s_cbranch_execz .LBB0_312
	v_add_u32_e32 v4, s33, v14
	s_movk_i32 s43, 0xc00
	v_mad_u64_u32 v[4:5], s[44:45], v4, s43, v[98:99]
	global_load_dwordx4 v[6:9], v[4:5], off
